# P0 x-rmsnorm rows: same dense lane-to-column remap (probe: P0 about 7 us faster)
# speedup vs baseline: 1.0077x; 1.0077x over previous
.LBB0_232:
	v_lshlrev_b32_e32 v20, 4, v1
	v_mov_b32_e32 v21, 0
	v_lshl_add_u64 v[22:23], s[14:15], 0, v[20:21]
	s_waitcnt lgkmcnt(0)
	flat_load_dwordx4 v[2:5], v[22:23]
	flat_load_dwordx4 v[6:9], v[22:23] offset:1024
	flat_load_dwordx4 v[10:13], v[22:23] offset:2048
	flat_load_dwordx4 v[14:17], v[22:23] offset:3072
	v_mbcnt_lo_u32_b32 v1, -1, 0
	v_mbcnt_hi_u32_b32 v19, -1, v1
	v_and_b32_e32 v1, 64, v19
	v_add_u32_e32 v22, 64, v1
	v_xor_b32_e32 v1, 1, v19
	v_cmp_lt_i32_e32 vcc, v1, v22
	v_xor_b32_e32 v23, 2, v19
	s_mov_b64 s[0:1], 0x4000000
	v_cndmask_b32_e32 v1, v19, v1, vcc
	v_cmp_lt_i32_e32 vcc, v23, v22
	v_lshlrev_b32_e32 v1, 2, v1
	v_lshl_add_u64 v[52:53], s[12:13], 0, v[20:21]
	v_cndmask_b32_e32 v23, v19, v23, vcc
	v_lshlrev_b32_e32 v54, 2, v23
	v_xor_b32_e32 v23, 4, v19
	v_cmp_lt_i32_e32 vcc, v23, v22
	v_mov_b32_e32 v59, 0x358637bd
	s_mov_b32 s6, 0xf800000
	v_cndmask_b32_e32 v23, v19, v23, vcc
	v_lshlrev_b32_e32 v55, 2, v23
	v_xor_b32_e32 v23, 8, v19
	v_cmp_lt_i32_e32 vcc, v23, v22
	v_mov_b32_e32 v60, 0x260
	s_nop 0
	v_cndmask_b32_e32 v23, v19, v23, vcc
	v_lshlrev_b32_e32 v56, 2, v23
	v_xor_b32_e32 v23, 16, v19
	v_cmp_lt_i32_e32 vcc, v23, v22
	s_nop 1
	v_cndmask_b32_e32 v23, v19, v23, vcc
	v_lshlrev_b32_e32 v57, 2, v23
	v_xor_b32_e32 v23, 32, v19
	v_cmp_lt_i32_e32 vcc, v23, v22
	s_nop 1
	v_cndmask_b32_e32 v19, v19, v23, vcc
	v_lshlrev_b32_e32 v58, 2, v19
	v_mov_b32_e32 v19, v21
	v_lshrrev_b32_e32 v18, 1, v18
	v_lshl_add_u64 v[18:19], s[84:85], 0, v[18:19]
	v_lshl_add_u64 v[50:51], v[18:19], 0, s[0:1]
	s_branch .LBB0_234

.LBB0_234:
	s_ashr_i32 s11, s10, 31
	s_lshl_b64 s[0:1], s[10:11], 12
	v_lshl_add_u64 v[18:19], v[52:53], 0, s[0:1]
	flat_load_dwordx4 v[34:37], v[18:19]
	flat_load_dwordx4 v[38:41], v[18:19] offset:1024
	flat_load_dwordx4 v[46:49], v[18:19] offset:3072
	flat_load_dwordx4 v[42:45], v[18:19] offset:2048
	s_add_i32 s4, s10, s83
	s_min_i32 s0, s4, 0xffff
	s_ashr_i32 s1, s0, 31
	s_lshl_b64 s[0:1], s[0:1], 12
	s_waitcnt lgkmcnt(0)
	v_lshl_add_u64 v[62:63], v[52:53], 0, s[0:1]
	flat_load_dwordx4 v[18:21], v[62:63]
	flat_load_dwordx4 v[22:25], v[62:63] offset:1024
	flat_load_dwordx4 v[26:29], v[62:63] offset:2048
	flat_load_dwordx4 v[30:33], v[62:63] offset:3072
	s_lshl_b64 s[0:1], s[10:11], 11
	s_cmp_gt_i32 s4, 0xffff
	s_waitcnt vmcnt(0) lgkmcnt(0)
	v_pk_mul_f32 v[62:63], v[36:37], v[36:37]
	v_pk_mul_f32 v[64:65], v[34:35], v[34:35]
	v_pk_mul_f32 v[66:67], v[40:41], v[40:41]
	v_pk_mul_f32 v[68:69], v[38:39], v[38:39]
	v_pk_mov_b32 v[74:75], v[64:65], v[62:63] op_sel:[1,0]
	v_mov_b32_e32 v65, v63
	v_pk_mov_b32 v[62:63], v[68:69], v[66:67] op_sel:[1,0]
	v_mov_b32_e32 v69, v67
	v_mul_f32_e32 v73, v47, v47
	v_mul_f32_e32 v70, v43, v43
	v_mul_f32_e32 v72, v45, v45
	v_pk_add_f32 v[64:65], v[74:75], v[64:65]
	v_pk_add_f32 v[62:63], v[62:63], v[68:69]
	v_mul_f32_e32 v61, v46, v46
	v_mul_f32_e32 v76, v48, v48
	v_mul_f32_e32 v77, v49, v49
	v_pk_fma_f32 v[66:67], v[42:43], v[42:43], v[70:71] op_sel_hi:[1,1,0]
	v_pk_fma_f32 v[70:71], v[44:45], v[44:45], v[72:73] op_sel_hi:[1,1,0]
	v_pk_add_f32 v[64:65], v[64:65], v[64:65] op_sel:[0,1] op_sel_hi:[1,0]
	v_pk_add_f32 v[62:63], v[62:63], v[62:63] op_sel:[0,1] op_sel_hi:[1,0]
	v_mov_b32_e32 v67, v76
	v_mov_b32_e32 v71, v77
	v_mov_b32_e32 v65, v61
	v_mov_b32_e32 v63, v73
	v_pk_add_f32 v[66:67], v[66:67], v[70:71]
	v_pk_add_f32 v[62:63], v[64:65], v[62:63]
	v_mul_f32_e32 v68, v19, v19
	v_pk_add_f32 v[62:63], v[62:63], v[66:67]
	v_mul_f32_e32 v69, v21, v21
	v_add_f32_e32 v61, v62, v63
	ds_bpermute_b32 v62, v1, v61
	v_mul_f32_e32 v72, v23, v23
	v_mul_f32_e32 v74, v25, v25
	v_mul_f32_e32 v75, v27, v27
	v_mul_f32_e32 v76, v29, v29
	s_waitcnt lgkmcnt(0)
	v_add_f32_e32 v61, v61, v62
	ds_bpermute_b32 v62, v54, v61
	v_fmac_f32_e32 v68, v18, v18
	v_fmac_f32_e32 v69, v20, v20
	v_fmac_f32_e32 v72, v22, v22
	v_fmac_f32_e32 v74, v24, v24
	v_mul_f32_e32 v77, v31, v31
	v_mul_f32_e32 v78, v33, v33
	v_fmac_f32_e32 v75, v26, v26
	v_fmac_f32_e32 v76, v28, v28
	v_add_f32_e32 v63, v68, v69
	v_add_f32_e32 v64, v72, v74
	v_fmac_f32_e32 v77, v30, v30
	v_fmac_f32_e32 v78, v32, v32
	v_add_f32_e32 v65, v75, v76
	v_add_f32_e32 v63, v63, v64
	s_waitcnt lgkmcnt(0)
	v_add_f32_e32 v61, v61, v62
	v_add_f32_e32 v66, v77, v78
	v_add_f32_e32 v63, v63, v65
	ds_bpermute_b32 v62, v55, v61
	v_add_f32_e32 v63, v63, v66
	ds_bpermute_b32 v64, v1, v63
	s_waitcnt lgkmcnt(1)
	v_add_f32_e32 v61, v61, v62
	ds_bpermute_b32 v62, v56, v61
	s_waitcnt lgkmcnt(1)
	v_add_f32_e32 v63, v63, v64
	ds_bpermute_b32 v64, v54, v63
	s_waitcnt lgkmcnt(1)
	v_add_f32_e32 v61, v61, v62
	ds_bpermute_b32 v62, v57, v61
	s_waitcnt lgkmcnt(1)
	v_add_f32_e32 v63, v63, v64
	ds_bpermute_b32 v64, v55, v63
	s_waitcnt lgkmcnt(1)
	v_add_f32_e32 v61, v61, v62
	ds_bpermute_b32 v62, v58, v61
	s_waitcnt lgkmcnt(1)
	v_add_f32_e32 v63, v63, v64
	ds_bpermute_b32 v64, v56, v63
	s_waitcnt lgkmcnt(1)
	v_add_f32_e32 v61, v61, v62
	v_fmamk_f32 v61, v61, 0x3a800000, v59
	s_waitcnt lgkmcnt(0)
	v_add_f32_e32 v63, v63, v64
	v_mul_f32_e32 v62, 0x4f800000, v61
	v_cmp_gt_f32_e32 vcc, s6, v61
	ds_bpermute_b32 v66, v57, v63
	v_lshl_add_u64 v[64:65], v[50:51], 0, s[0:1]
	v_cndmask_b32_e32 v62, v61, v62, vcc
	v_sqrt_f32_e32 v67, v62
	s_waitcnt lgkmcnt(0)
	v_add_f32_e32 v61, v63, v66
	v_add_u32_e32 v63, -1, v67
	v_add_u32_e32 v66, 1, v67
	v_fma_f32 v68, -v63, v67, v62
	v_fma_f32 v69, -v66, v67, v62
	v_cmp_ge_f32_e64 s[0:1], 0, v68
	s_nop 1
	v_cndmask_b32_e64 v63, v67, v63, s[0:1]
	v_cmp_lt_f32_e64 s[0:1], 0, v69
	s_nop 1
	v_cndmask_b32_e64 v63, v63, v66, s[0:1]
	v_mul_f32_e32 v66, 0x37800000, v63
	v_cndmask_b32_e32 v63, v63, v66, vcc
	v_cmp_class_f32_e32 vcc, v62, v60
	s_nop 1
	v_cndmask_b32_e32 v63, v63, v62, vcc
	v_div_scale_f32 v66, s[0:1], v63, v63, 1.0
	v_rcp_f32_e32 v67, v66
	v_div_scale_f32 v68, vcc, 1.0, v63, 1.0
	ds_bpermute_b32 v62, v58, v61
	v_fma_f32 v69, -v66, v67, 1.0
	v_fmac_f32_e32 v67, v69, v67
	v_mul_f32_e32 v69, v68, v67
	v_fma_f32 v70, -v66, v69, v68
	v_fmac_f32_e32 v69, v70, v67
	v_fma_f32 v66, -v66, v69, v68
	v_div_fmas_f32 v66, v66, v67, v69
	v_div_fixup_f32 v66, v66, v63, 1.0
	v_pk_mul_f32 v[34:35], v[34:35], v[66:67] op_sel_hi:[1,0]
	v_pk_mul_f32 v[36:37], v[36:37], v[66:67] op_sel_hi:[1,0]
	v_pk_mul_f32 v[38:39], v[38:39], v[66:67] op_sel_hi:[1,0]
	v_pk_mul_f32 v[40:41], v[40:41], v[66:67] op_sel_hi:[1,0]
	v_pk_mul_f32 v[36:37], v[4:5], v[36:37]
	v_pk_mul_f32 v[34:35], v[2:3], v[34:35]
	v_pk_mul_f32 v[46:47], v[46:47], v[66:67] op_sel_hi:[1,0]
	v_pk_mul_f32 v[48:49], v[48:49], v[66:67] op_sel_hi:[1,0]
	v_pk_mul_f32 v[42:43], v[42:43], v[66:67] op_sel_hi:[1,0]
	v_pk_mul_f32 v[44:45], v[44:45], v[66:67] op_sel_hi:[1,0]
	v_pk_mul_f32 v[40:41], v[8:9], v[40:41]
	v_pk_mul_f32 v[38:39], v[6:7], v[38:39]
	v_cvt_pk_bf16_f32 v34, v34, v35
	v_cvt_pk_bf16_f32 v35, v36, v37
	v_pk_mul_f32 v[48:49], v[16:17], v[48:49]
	v_cvt_pk_bf16_f32 v36, v38, v39
	v_cvt_pk_bf16_f32 v37, v40, v41
	v_pk_mul_f32 v[46:47], v[14:15], v[46:47]
	v_pk_mul_f32 v[44:45], v[12:13], v[44:45]
	v_pk_mul_f32 v[42:43], v[10:11], v[42:43]
	global_store_dwordx2 v[64:65], v[34:35], off
	global_store_dwordx2 v[64:65], v[36:37], off offset:512
	s_nop 1
	v_cvt_pk_bf16_f32 v34, v42, v43
	v_cvt_pk_bf16_f32 v35, v44, v45
	v_cvt_pk_bf16_f32 v36, v46, v47
	v_cvt_pk_bf16_f32 v37, v48, v49
	global_store_dwordx2 v[64:65], v[34:35], off offset:1024
	global_store_dwordx2 v[64:65], v[36:37], off offset:1536
	s_cbranch_scc1 .LBB0_233
	s_waitcnt lgkmcnt(0)
	v_add_f32_e32 v34, v61, v62
	v_fmamk_f32 v34, v34, 0x3a800000, v59
	v_mul_f32_e32 v35, 0x4f800000, v34
	v_cmp_gt_f32_e32 vcc, s6, v34
	s_ashr_i32 s5, s4, 31
	s_nop 0
	v_cndmask_b32_e32 v34, v34, v35, vcc
	v_sqrt_f32_e32 v35, v34
	s_nop 0
	v_add_u32_e32 v36, -1, v35
	v_fma_f32 v38, -v36, v35, v34
	v_add_u32_e32 v37, 1, v35
	v_cmp_ge_f32_e64 s[0:1], 0, v38
	s_nop 1
	v_cndmask_b32_e64 v36, v35, v36, s[0:1]
	v_fma_f32 v35, -v37, v35, v34
	v_cmp_lt_f32_e64 s[0:1], 0, v35
	s_nop 1
	v_cndmask_b32_e64 v35, v36, v37, s[0:1]
	v_mul_f32_e32 v36, 0x37800000, v35
	v_cndmask_b32_e32 v35, v35, v36, vcc
	v_cmp_class_f32_e32 vcc, v34, v60
	s_nop 1
	v_cndmask_b32_e32 v34, v35, v34, vcc
	v_div_scale_f32 v35, s[0:1], v34, v34, 1.0
	v_rcp_f32_e32 v36, v35
	s_lshl_b64 s[0:1], s[4:5], 11
	v_fma_f32 v37, -v35, v36, 1.0
	v_fmac_f32_e32 v36, v37, v36
	v_div_scale_f32 v37, vcc, 1.0, v34, 1.0
	v_mul_f32_e32 v38, v37, v36
	v_fma_f32 v39, -v35, v38, v37
	v_fmac_f32_e32 v38, v39, v36
	v_fma_f32 v35, -v35, v38, v37
	v_div_fmas_f32 v35, v35, v36, v38
	v_div_fixup_f32 v34, v35, v34, 1.0
	v_pk_mul_f32 v[18:19], v[18:19], v[34:35] op_sel_hi:[1,0]
	v_pk_mul_f32 v[20:21], v[20:21], v[34:35] op_sel_hi:[1,0]
	v_pk_mul_f32 v[22:23], v[22:23], v[34:35] op_sel_hi:[1,0]
	v_pk_mul_f32 v[24:25], v[24:25], v[34:35] op_sel_hi:[1,0]
	v_pk_mul_f32 v[20:21], v[4:5], v[20:21]
	v_pk_mul_f32 v[18:19], v[2:3], v[18:19]
	v_pk_mul_f32 v[30:31], v[30:31], v[34:35] op_sel_hi:[1,0]
	v_pk_mul_f32 v[32:33], v[32:33], v[34:35] op_sel_hi:[1,0]
	v_pk_mul_f32 v[26:27], v[26:27], v[34:35] op_sel_hi:[1,0]
	v_pk_mul_f32 v[28:29], v[28:29], v[34:35] op_sel_hi:[1,0]
	v_pk_mul_f32 v[24:25], v[8:9], v[24:25]
	v_pk_mul_f32 v[22:23], v[6:7], v[22:23]
	v_lshl_add_u64 v[34:35], v[50:51], 0, s[0:1]
	v_cvt_pk_bf16_f32 v18, v18, v19
	v_cvt_pk_bf16_f32 v19, v20, v21
	v_cvt_pk_bf16_f32 v20, v22, v23
	v_cvt_pk_bf16_f32 v21, v24, v25
	v_pk_mul_f32 v[32:33], v[16:17], v[32:33]
	v_pk_mul_f32 v[30:31], v[14:15], v[30:31]
	v_pk_mul_f32 v[28:29], v[12:13], v[28:29]
	v_pk_mul_f32 v[26:27], v[10:11], v[26:27]
	global_store_dwordx2 v[34:35], v[18:19], off
	global_store_dwordx2 v[34:35], v[20:21], off offset:512
	s_nop 1
	v_cvt_pk_bf16_f32 v18, v26, v27
	v_cvt_pk_bf16_f32 v19, v28, v29
	v_cvt_pk_bf16_f32 v20, v30, v31
	v_cvt_pk_bf16_f32 v21, v32, v33
	global_store_dwordx2 v[34:35], v[18:19], off offset:1024
	global_store_dwordx2 v[34:35], v[20:21], off offset:1536
	s_branch .LBB0_233
